# attention unit prologue: work-queue atomic and T5-bias gather no longer waited before the Q/KV loads are issued (results parked in dead regs)
# baseline (speedup 1.0000x reference)
; __global__ void __launch_bounds__(512, 2) fwd_mega(Args a) {
;     ...
;                 while (u < 1536) {
;                     int nxt = 0;
;                     if (tid == 0) nxt = (int)atomicAdd(ctr, 1u);
;                     attn_unit(lds, P, OG, LSE, a.in[12], u);
;                     if (tid == 0) s_unit[par ^ 1] = nxt;
.LBB0_407:
	v_mov_b32_e32 v182, 0
	s_and_saveexec_b64 s[4:5], s[0:1]
	s_cbranch_execz .LBB0_411
	s_mov_b64 s[8:9], exec
	v_mbcnt_lo_u32_b32 v0, s8, 0
	v_mbcnt_hi_u32_b32 v0, s9, v0
	v_cmp_eq_u32_e32 vcc, 0, v0
	s_and_saveexec_b64 s[6:7], vcc
	s_cbranch_execz .LBB0_410
	s_bcnt1_i32_b64 s8, s[8:9]
	v_mov_b32_e32 v2, s8
	global_atomic_add v219, v1, v2, s[2:3] sc0

; DI void attn_unit(LAS unsigned char* lds, const bf16* P, bf16* OG, float* LSE, const float* relb, int u) {
;     ...
;     for (int jj = 0; jj < 2; ++jj) { const int j = htid + 256 * jj;
;         if (j < 320) { const int delta = j - 96; float val = -1e30f;
;             if (delta >= 0 && delta <= 128) { const int dist = delta * dil; int bucket;
;                 if (dist < 16) bucket = dist; else { const float d = (float)dist; int lg = 16 + (int)(logf(d / 16.0f) / logf(128.0f) * 16.0f); bucket = lg < 31 ? lg : 31; }
;                 val = relb[bucket * 12 + head] * 1.4426950408889634f; }
;             biasT[j] = val; } }
; __global__ void __launch_bounds__(512, 2) fwd_mega(Args a) {
;     ...
;                     if (tid == 0) nxt = (int)atomicAdd(ctr, 1u);
.LBB0_411:
	s_or_b64 exec, exec, s[4:5]
	s_ashr_i32 s4, s18, 3
	s_mul_hi_i32 s5, s4, 0x2aaaaaab
	s_lshr_b32 s6, s5, 31
	s_ashr_i32 s5, s5, 1
	s_add_i32 s8, s5, s6
	s_mul_i32 s5, s8, 12
	s_sub_i32 s4, s4, s5
	v_mov_b32_e32 v8, v188
	s_ashr_i32 s6, s4, 2
	s_cmp_lt_u32 s4, 4
	v_and_b32_e32 v4, 0xff, v8
	s_cselect_b64 s[14:15], -1, 0
	s_cmp_eq_u32 s6, 1
	v_add_u32_e32 v2, 0xffffffa0, v4
	s_movk_i32 s5, 0x81
	v_readfirstlane_b32 s24, v8
	s_cselect_b64 s[16:17], -1, 0
	v_cmp_gt_u32_e32 vcc, s5, v2
	v_mov_b32_e32 v0, 0xf149f2ca
	s_mov_b64 s[98:99], vcc
	s_and_saveexec_b64 s[10:11], vcc
	s_cbranch_execz .LBB0_415
	s_and_b64 s[12:13], s[16:17], exec
	s_cselect_b32 s5, 2, 4
	s_and_b64 s[12:13], s[14:15], exec
	s_cselect_b32 s5, 0, s5
	v_lshlrev_b32_e32 v0, s5, v2
	v_cmp_lt_u32_e32 vcc, 15, v0
	s_and_saveexec_b64 s[12:13], vcc
	s_cbranch_execz .LBB0_414
	v_cvt_f32_u32_e32 v0, v0
	s_mov_b32 s5, 0x800000
	v_mul_f32_e32 v0, 0x3d800000, v0
	v_cmp_gt_f32_e32 vcc, s5, v0
	s_mov_b32 s5, 0x3f317217
	s_nop 0
	v_cndmask_b32_e64 v2, 0, 32, vcc
	v_ldexp_f32 v0, v0, v2
	v_log_f32_e32 v0, v0
	v_cndmask_b32_e32 v2, 0, v195, vcc
	v_mul_f32_e32 v3, 0x3f317217, v0
	v_fma_f32 v3, v0, s5, -v3
	v_fmac_f32_e32 v3, 0x3377d1cf, v0
	s_mov_b32 s5, 0x7f800000
	v_fmac_f32_e32 v3, 0x3f317217, v0
	v_cmp_lt_f32_e64 vcc, |v0|, s5
	s_mov_b32 s5, 0x409b43d5
	s_nop 0
	v_cndmask_b32_e32 v0, v0, v3, vcc
	v_sub_f32_e32 v0, v0, v2
	v_div_scale_f32 v2, s[20:21], s5, s5, v0
	v_rcp_f32_e32 v3, v2
	v_div_scale_f32 v5, vcc, v0, s5, v0
	v_fma_f32 v6, -v2, v3, 1.0
	v_fmac_f32_e32 v3, v6, v3
	v_mul_f32_e32 v6, v5, v3
	v_fma_f32 v7, -v2, v6, v5
	v_fmac_f32_e32 v6, v7, v3
	v_fma_f32 v2, -v2, v6, v5
	v_div_fmas_f32 v2, v2, v3, v6
	v_div_fixup_f32 v0, v2, s5, v0
	v_mul_f32_e32 v0, 0x41800000, v0
	v_cvt_i32_f32_e32 v0, v0
	v_min_i32_e32 v0, 15, v0
	v_add_u32_e32 v0, 16, v0
.LBB0_414:
	s_or_b64 exec, exec, s[12:13]
	v_mov_b32_e32 v2, s4
	v_mad_u64_u32 v[2:3], s[12:13], v0, 12, v[2:3]
	v_readlane_b32 s68, v251, 16
	v_ashrrev_i32_e32 v3, 31, v2
	v_readlane_b32 s76, v251, 24
	v_readlane_b32 s77, v251, 25
	v_readlane_b32 s69, v251, 17
	v_readlane_b32 s70, v251, 18
	v_lshl_add_u64 v[2:3], v[2:3], 2, s[76:77]
	global_load_dword v216, v[2:3], off
	v_readlane_b32 s71, v251, 19
	v_readlane_b32 s72, v251, 20
	v_readlane_b32 s73, v251, 21
	v_readlane_b32 s74, v251, 22
	v_readlane_b32 s75, v251, 23
	v_readlane_b32 s78, v251, 26
	v_readlane_b32 s79, v251, 27
	v_readlane_b32 s80, v251, 28
	v_readlane_b32 s81, v251, 29
	v_readlane_b32 s82, v251, 30
	v_readlane_b32 s83, v251, 31
.LBB0_415:
	s_or_b64 exec, exec, s[10:11]
	s_ashr_i32 s5, s24, 8
	s_mul_i32 s25, s5, 0x9900
	s_add_i32 s26, s25, 0
	v_lshl_add_u32 v2, v4, 2, s26
	v_mov_b32_e32 v217, v2
	v_or_b32_e32 v0, 0x100, v4
	s_movk_i32 s7, 0x140
	v_cmp_gt_u32_e32 vcc, s7, v0
	s_and_saveexec_b64 s[10:11], vcc
	ds_write_b32 v2, v193 offset:38912
	s_or_b64 exec, exec, s[10:11]
	s_and_b64 s[10:11], s[16:17], exec
	s_cselect_b32 s7, 2, 0
	s_and_b64 s[10:11], s[14:15], exec
	s_cselect_b32 s7, 4, s7
	s_lshl_b32 s9, s18, 1
	s_and_b32 s9, s9, 14
	s_add_i32 s5, s5, s9
	s_lshl_b32 s10, -1, s7
	s_ashr_i32 s9, s8, 31
	s_ashr_i32 s28, s5, s7
	s_andn2_b32 s5, s5, s10
	s_lshl_b64 s[18:19], s[8:9], 11
	s_cmp_eq_u32 s6, 2
	s_cselect_b32 s27, 2, 0
	s_lshl_b32 s7, s5, 7
	s_lshl_b32 s23, s27, 6
	s_add_i32 s29, s7, s23
	s_addk_i32 s29, 0xff80
	s_cmp_gt_i32 s29, -1
	v_and_b32_e32 v9, 3, v8
	s_cbranch_scc1 .LBB0_419
	s_and_b64 s[8:9], s[16:17], exec
	s_cselect_b32 s5, 2, 4
	s_and_b64 s[8:9], s[14:15], exec
	s_cselect_b32 s8, 0, s5
	s_ashr_i32 s5, s28, 31
	s_add_u32 s10, s18, s28
	s_addc_u32 s11, s19, s5
	s_lshl_b32 s5, s4, 7
	v_readlane_b32 s20, v254, 6
	s_add_i32 s12, s5, 0x600
	v_readlane_b32 s21, v254, 7
	s_and_b32 s9, s5, 0x80
	s_mov_b32 s35, s21
	s_lshr_b32 s34, s12, 8
	s_lshl_b64 s[12:13], s[34:35], 24
	s_mov_b32 s34, s9
	v_lshl_or_b32 v0, v9, 5, s9
	v_writelane_b32 v254, s34, 6
	s_mov_b64 s[20:21], 0
	v_mov_b64_e32 v[2:3], v[0:1]
	v_writelane_b32 v254, s35, 7
	s_andn2_b64 vcc, exec, s[20:21]
	v_lshrrev_b32_e32 v10, 2, v4
	s_cbranch_vccnz .LBB0_421
	s_branch .LBB0_420

; DI size_t pidx(size_t row, int col) { return (size_t)(col >> 8) * ((size_t)TH * 256) + row * 256 + (size_t)(col & 255); }
; DI float lo_f(unsigned u) { return __uint_as_float(u << 16); }
; DI float hi_f(unsigned u) { return __uint_as_float(u & 0xffff0000u); }
; DI void attn_unit(LAS unsigned char* lds, const bf16* P, bf16* OG, float* LSE, const float* relb, int u) {
;     ...
;     const int qmin = 128 * qb + 32 * w, qsub = qmin + r32; const size_t qtok = rowb + (size_t)qsub * dil + r;
;     bf16x8 qf[8];
;     { const bf16* qrow = P + pidx(qtok, head * 128); v4u qraw[8]; float ss = 0.f;
; #pragma unroll
;         for (int kk = 0; kk < 8; ++kk) { qraw[kk] = *(const v4u*)(qrow + 16 * kk + 8 * hh); const v4u q = qraw[kk];
;             ss += lo_f(q.x) * lo_f(q.x) + hi_f(q.x) * hi_f(q.x) + lo_f(q.y) * lo_f(q.y) + hi_f(q.y) * hi_f(q.y) + lo_f(q.z) * lo_f(q.z) + hi_f(q.z) * hi_f(q.z) + lo_f(q.w) * lo_f(q.w) + hi_f(q.w) * hi_f(q.w); }
;         ss += __shfl_xor(ss, 32);
.LBB0_421:
	s_lshr_b32 s9, s24, 1
	s_and_b32 s14, s9, 0x60
	v_and_b32_e32 v11, 31, v8
	s_or_b32 s9, s7, s14
	s_ashr_i32 s16, s4, 1
	v_or_b32_e32 v0, s9, v11
	s_ashr_i32 s17, s16, 31
	v_lshlrev_b64 v[4:5], s8, v[0:1]
	s_lshl_b64 s[16:17], s[16:17], 24
	v_lshl_add_u64 v[178:179], v[4:5], 0, s[10:11]
	s_add_u32 s16, s86, s16
	s_addc_u32 s17, s87, s17
	v_lshlrev_b64 v[4:5], 9, v[178:179]
	v_lshl_add_u64 v[4:5], s[16:17], 0, v[4:5]
	v_readlane_b32 s16, v254, 6
	v_bfe_u32 v183, v8, 5, 1
	v_readlane_b32 s17, v254, 7
	v_lshlrev_b32_e32 v0, 4, v183
	s_mov_b32 s15, 0x800000
	v_lshl_add_u64 v[4:5], s[16:17], 1, v[4:5]
	v_lshl_add_u64 v[36:37], v[4:5], 0, v[0:1]
	global_load_dwordx4 v[4:7], v[36:37], off offset:32
	global_load_dwordx4 v[12:15], v[36:37], off
	global_load_dwordx4 v[16:19], v[36:37], off offset:96
	global_load_dwordx4 v[20:23], v[36:37], off offset:64
	global_load_dwordx4 v[24:27], v[36:37], off offset:160
	global_load_dwordx4 v[28:31], v[36:37], off offset:128
	global_load_dwordx4 v[32:35], v[36:37], off offset:224
	s_nop 0
	global_load_dwordx4 v[36:39], v[36:37], off offset:192
	s_add_u32 s12, s86, s12
	s_addc_u32 s13, s87, s13
	v_lshl_add_u64 v[180:181], v[2:3], 1, s[12:13]
	v_lshlrev_b32_e32 v2, 2, v8
	v_lshlrev_b32_e32 v185, 2, v183
	s_lshl_b32 s13, s24, 1
	s_and_b32 s13, s13, 0x180
	s_add_i32 s25, s25, s13
	s_movk_i32 s16, 0x110
	s_lshl_b32 s13, s27, 8
	v_mov_b32_e32 v3, v1
	s_add_i32 s12, s27, -1
	v_mov_b32_e32 v206, 0xf149f2ca
	v_mov_b32_e32 v205, 0
	s_waitcnt vmcnt(7)
	v_and_b32_e32 v43, 0xffff0000, v4
	s_waitcnt vmcnt(6)
	v_and_b32_e32 v42, 0xffff0000, v12
	v_lshlrev_b32_e32 v41, 16, v4
	v_lshlrev_b32_e32 v40, 16, v12
	v_lshlrev_b32_e32 v49, 16, v6
	v_and_b32_e32 v51, 0xffff0000, v6
	v_lshlrev_b32_e32 v53, 16, v7
	v_and_b32_e32 v55, 0xffff0000, v7
	v_pk_mul_f32 v[6:7], v[42:43], v[42:43]
	v_lshlrev_b32_e32 v45, 16, v5
	v_lshlrev_b32_e32 v44, 16, v13
	v_pk_fma_f32 v[6:7], v[40:41], v[40:41], v[6:7]
	v_and_b32_e32 v47, 0xffff0000, v5
	v_and_b32_e32 v46, 0xffff0000, v13
	s_waitcnt vmcnt(5)
	v_and_b32_e32 v59, 0xffff0000, v16
	s_waitcnt vmcnt(4)
	v_and_b32_e32 v58, 0xffff0000, v20
	v_pk_fma_f32 v[6:7], v[44:45], v[44:45], v[6:7]
	v_lshlrev_b32_e32 v48, 16, v14
	v_lshlrev_b32_e32 v57, 16, v16
	v_lshlrev_b32_e32 v56, 16, v20
	v_pk_mul_f32 v[12:13], v[58:59], v[58:59]
	v_pk_fma_f32 v[6:7], v[46:47], v[46:47], v[6:7]
	v_and_b32_e32 v50, 0xffff0000, v14
	v_lshlrev_b32_e32 v61, 16, v17
	v_lshlrev_b32_e32 v60, 16, v21
	s_waitcnt vmcnt(3)
	v_and_b32_e32 v71, 0xffff0000, v24
	s_waitcnt vmcnt(2)
	v_and_b32_e32 v70, 0xffff0000, v28
	v_pk_fma_f32 v[12:13], v[56:57], v[56:57], v[12:13]
	v_pk_fma_f32 v[6:7], v[48:49], v[48:49], v[6:7]
	v_lshlrev_b32_e32 v52, 16, v15
	v_and_b32_e32 v54, 0xffff0000, v15
	v_and_b32_e32 v63, 0xffff0000, v17
	v_and_b32_e32 v62, 0xffff0000, v21
	v_lshlrev_b32_e32 v20, 16, v22
	v_and_b32_e32 v64, 0xffff0000, v22
	v_lshlrev_b32_e32 v66, 16, v23
	v_and_b32_e32 v68, 0xffff0000, v23
	v_lshlrev_b32_e32 v23, 16, v24
	v_lshlrev_b32_e32 v22, 16, v28
	v_pk_mul_f32 v[14:15], v[70:71], v[70:71]
	v_pk_fma_f32 v[12:13], v[60:61], v[60:61], v[12:13]
	v_pk_fma_f32 v[6:7], v[50:51], v[50:51], v[6:7]
	v_lshlrev_b32_e32 v21, 16, v18
	v_lshlrev_b32_e32 v73, 16, v25
	v_lshlrev_b32_e32 v72, 16, v29
	v_pk_fma_f32 v[14:15], v[22:23], v[22:23], v[14:15]
	v_pk_fma_f32 v[12:13], v[62:63], v[62:63], v[12:13]
	v_pk_fma_f32 v[6:7], v[52:53], v[52:53], v[6:7]
	v_and_b32_e32 v65, 0xffff0000, v18
	v_and_b32_e32 v25, 0xffff0000, v25
	v_and_b32_e32 v24, 0xffff0000, v29
	v_pk_fma_f32 v[14:15], v[72:73], v[72:73], v[14:15]
	v_pk_fma_f32 v[12:13], v[20:21], v[20:21], v[12:13]
	v_pk_fma_f32 v[16:17], v[54:55], v[54:55], v[6:7]
	s_waitcnt vmcnt(1)
	v_and_b32_e32 v7, 0xffff0000, v32
	s_waitcnt vmcnt(0)
	v_mov_b32_e32 v218, 0xf149f2ca
	v_mul_f32_e32 v216, 0x3fb8aa3b, v216
	v_cndmask_b32_e64 v218, v218, v216, s[98:99]
	ds_write_b32 v217, v218 offset:37888
	s_mov_b64 s[100:101], exec
	s_and_b64 exec, exec, s[0:1]
	v_mov_b32_e32 v182, v219
	s_mov_b64 exec, s[100:101]
	v_and_b32_e32 v6, 0xffff0000, v36
	v_lshlrev_b32_e32 v67, 16, v19
	v_and_b32_e32 v69, 0xffff0000, v19
	v_lshlrev_b32_e32 v29, 16, v26
	v_lshlrev_b32_e32 v28, 16, v30
	v_lshlrev_b32_e32 v5, 16, v32
	v_pk_fma_f32 v[14:15], v[24:25], v[24:25], v[14:15]
	v_pk_fma_f32 v[12:13], v[64:65], v[64:65], v[12:13]
	v_lshlrev_b32_e32 v4, 16, v36
	v_pk_mul_f32 v[18:19], v[6:7], v[6:7]
	v_and_b32_e32 v75, 0xffff0000, v26
	v_and_b32_e32 v74, 0xffff0000, v30
	v_lshlrev_b32_e32 v76, 16, v31
	v_and_b32_e32 v26, 0xffff0000, v31
	v_pk_fma_f32 v[14:15], v[28:29], v[28:29], v[14:15]
	v_pk_fma_f32 v[12:13], v[66:67], v[66:67], v[12:13]
	v_pk_fma_f32 v[18:19], v[4:5], v[4:5], v[18:19]
	v_lshlrev_b32_e32 v31, 16, v33
	v_lshlrev_b32_e32 v30, 16, v37
	v_lshlrev_b32_e32 v77, 16, v27
	v_pk_fma_f32 v[14:15], v[74:75], v[74:75], v[14:15]
	v_pk_fma_f32 v[12:13], v[68:69], v[68:69], v[12:13]
	v_pk_fma_f32 v[18:19], v[30:31], v[30:31], v[18:19]
	v_and_b32_e32 v33, 0xffff0000, v33
	v_and_b32_e32 v32, 0xffff0000, v37
	v_add_f32_e32 v16, v16, v17
	v_and_b32_e32 v27, 0xffff0000, v27
	v_pk_fma_f32 v[14:15], v[76:77], v[76:77], v[14:15]
	v_pk_fma_f32 v[18:19], v[32:33], v[32:33], v[18:19]
	v_lshlrev_b32_e32 v37, 16, v34
	v_lshlrev_b32_e32 v36, 16, v38
	v_add_f32_e32 v12, v16, v12
	v_pk_fma_f32 v[14:15], v[26:27], v[26:27], v[14:15]
	v_pk_fma_f32 v[18:19], v[36:37], v[36:37], v[18:19]
	v_and_b32_e32 v79, 0xffff0000, v34
	v_and_b32_e32 v78, 0xffff0000, v38
	v_add_f32_e32 v12, v12, v13
	v_pk_fma_f32 v[18:19], v[78:79], v[78:79], v[18:19]
	v_lshlrev_b32_e32 v81, 16, v35
	v_lshlrev_b32_e32 v80, 16, v39
	v_add_f32_e32 v12, v12, v14
	v_and_b32_e32 v14, 64, v194
	v_pk_fma_f32 v[18:19], v[80:81], v[80:81], v[18:19]
	v_and_b32_e32 v35, 0xffff0000, v35
	v_and_b32_e32 v34, 0xffff0000, v39
	v_xor_b32_e32 v13, 32, v194
	v_add_u32_e32 v38, 64, v14
	v_pk_fma_f32 v[18:19], v[34:35], v[34:35], v[18:19]
	v_add_f32_e32 v12, v12, v15
	v_cmp_lt_i32_e32 vcc, v13, v38
	v_add_f32_e32 v12, v12, v18
	v_add_f32_e32 v12, v12, v19
	v_cndmask_b32_e32 v13, v194, v13, vcc
	v_lshlrev_b32_e32 v184, 2, v13
	ds_bpermute_b32 v13, v184, v12
	s_waitcnt lgkmcnt(0)
; #define LAS __attribute__((address_space(3)))
; DI float lo_f(unsigned u) { return __uint_as_float(u << 16); }
; DI float hi_f(unsigned u) { return __uint_as_float(u & 0xffff0000u); }
; DI void attn_unit(LAS unsigned char* lds, const bf16* P, bf16* OG, float* LSE, const float* relb, int u) {
;     ...
;         const float rs = rsqrtf(ss * (1.0f / 128.0f) + 1e-6f) * (0.08838834764831845f * 1.4426950408889634f);
; #pragma unroll
;         for (int kk = 0; kk < 8; ++kk) { const v4u q = qraw[kk]; const f32x4 g0 = *(const LAS f32x4*)(gq + 16 * kk + 8 * hh), g1 = *(const LAS f32x4*)(gq + 16 * kk + 8 * hh + 4);
;             qf[kk] = pack8(lo_f(q.x) * rs * g0[0], hi_f(q.x) * rs * g0[1], lo_f(q.y) * rs * g0[2], hi_f(q.y) * rs * g0[3], lo_f(q.z) * rs * g1[0], hi_f(q.z) * rs * g1[1], lo_f(q.w) * rs * g1[2], hi_f(q.w) * rs * g1[3]); }
	v_add_f32_e32 v12, v12, v13
	v_fmamk_f32 v12, v12, 0x3c000000, v192
	v_mul_f32_e32 v13, 0x4b800000, v12
	v_cmp_gt_f32_e32 vcc, s15, v12
	s_movk_i32 s15, 0x140
	s_nop 0
	v_cndmask_b32_e32 v12, v12, v13, vcc
	v_rsq_f32_e32 v16, v12
	v_lshl_add_u32 v12, v183, 5, 0
	v_add_u32_e32 v39, 0x13200, v12
	ds_read_b128 v[12:15], v39
	v_mul_f32_e32 v17, 0x45800000, v16
	v_cndmask_b32_e32 v16, v16, v17, vcc
	v_mul_f32_e32 v82, 0x3e0293ee, v16
	ds_read_b128 v[16:19], v39 offset:16
	v_mul_f32_e32 v40, v82, v40
	s_waitcnt lgkmcnt(1)
	v_mul_f32_e32 v12, v12, v40
	v_mul_f32_e32 v40, v82, v42
	v_mul_f32_e32 v13, v13, v40
	v_mul_f32_e32 v40, v82, v44
	v_mul_f32_e32 v14, v14, v40
	v_mul_f32_e32 v40, v82, v46
	v_mul_f32_e32 v15, v15, v40
	v_mul_f32_e32 v40, v82, v48
	s_waitcnt lgkmcnt(0)
	v_mul_f32_e32 v16, v16, v40
	v_mul_f32_e32 v40, v82, v50
	v_mul_f32_e32 v17, v17, v40
	v_mul_f32_e32 v40, v82, v52
	v_mul_f32_e32 v18, v18, v40
	v_mul_f32_e32 v40, v82, v54
	v_mul_f32_e32 v19, v19, v40
	v_cvt_pk_bf16_f32 v130, v12, v13
	v_cvt_pk_bf16_f32 v131, v14, v15
	v_cvt_pk_bf16_f32 v132, v16, v17
	v_cvt_pk_bf16_f32 v133, v18, v19
	ds_read_b128 v[12:15], v39 offset:64
	ds_read_b128 v[16:19], v39 offset:80
	v_mul_f32_e32 v40, v82, v41
	v_mul_f32_e32 v20, v82, v20
	v_mul_f32_e32 v4, v82, v4
	s_waitcnt lgkmcnt(1)
	v_mul_f32_e32 v12, v12, v40
	v_mul_f32_e32 v40, v82, v43
	v_mul_f32_e32 v13, v13, v40
	v_mul_f32_e32 v40, v82, v45
	v_mul_f32_e32 v14, v14, v40
	v_mul_f32_e32 v40, v82, v47
	v_mul_f32_e32 v15, v15, v40
	v_mul_f32_e32 v40, v82, v49
	s_waitcnt lgkmcnt(0)
	v_mul_f32_e32 v16, v16, v40
	v_mul_f32_e32 v40, v82, v51
	v_mul_f32_e32 v17, v17, v40
	v_mul_f32_e32 v40, v82, v53
	v_mul_f32_e32 v18, v18, v40
	v_mul_f32_e32 v40, v82, v55
	v_mul_f32_e32 v19, v19, v40
	v_cvt_pk_bf16_f32 v134, v12, v13
	v_cvt_pk_bf16_f32 v135, v14, v15
	v_cvt_pk_bf16_f32 v136, v16, v17
	v_cvt_pk_bf16_f32 v137, v18, v19
	ds_read_b128 v[12:15], v39 offset:128
	ds_read_b128 v[16:19], v39 offset:144
	v_mul_f32_e32 v40, v82, v56
	v_mul_f32_e32 v6, v82, v6
	v_mul_f32_e32 v5, v82, v5
	s_waitcnt lgkmcnt(1)
	v_mul_f32_e32 v12, v12, v40
	v_mul_f32_e32 v40, v82, v58
	s_waitcnt lgkmcnt(0)
	v_mul_f32_e32 v16, v16, v20
	v_mul_f32_e32 v20, v82, v64
	v_mul_f32_e32 v13, v13, v40
	v_mul_f32_e32 v40, v82, v60
	v_mul_f32_e32 v17, v17, v20
	v_mul_f32_e32 v20, v82, v66
	v_mul_f32_e32 v14, v14, v40
	v_mul_f32_e32 v40, v82, v62
	v_mul_f32_e32 v18, v18, v20
	v_mul_f32_e32 v20, v82, v68
	v_mul_f32_e32 v15, v15, v40
	v_mul_f32_e32 v19, v19, v20
	v_cvt_pk_bf16_f32 v138, v12, v13
	v_cvt_pk_bf16_f32 v139, v14, v15
	v_cvt_pk_bf16_f32 v140, v16, v17
	v_cvt_pk_bf16_f32 v141, v18, v19
	ds_read_b128 v[12:15], v39 offset:192
	ds_read_b128 v[16:19], v39 offset:208
	v_mul_f32_e32 v20, v82, v57
	v_mul_f32_e32 v7, v82, v7
	s_waitcnt lgkmcnt(1)
	v_mul_f32_e32 v12, v20, v12
	v_mul_f32_e32 v20, v82, v59
	v_mul_f32_e32 v13, v20, v13
	v_mul_f32_e32 v20, v82, v61
	v_mul_f32_e32 v14, v20, v14
	v_mul_f32_e32 v20, v82, v63
	v_mul_f32_e32 v15, v20, v15
	v_mul_f32_e32 v20, v82, v21
	s_waitcnt lgkmcnt(0)
	v_mul_f32_e32 v16, v20, v16
	v_mul_f32_e32 v20, v82, v65
	v_mul_f32_e32 v17, v20, v17
	v_mul_f32_e32 v20, v82, v67
	v_mul_f32_e32 v18, v20, v18
	v_mul_f32_e32 v20, v82, v69
	v_mul_f32_e32 v19, v20, v19
	v_cvt_pk_bf16_f32 v142, v12, v13
	v_cvt_pk_bf16_f32 v143, v14, v15
	v_cvt_pk_bf16_f32 v144, v16, v17
	v_cvt_pk_bf16_f32 v145, v18, v19
	ds_read_b128 v[12:15], v39 offset:256
	ds_read_b128 v[16:19], v39 offset:272
	v_mul_f32_e32 v20, v82, v22
	s_waitcnt lgkmcnt(1)
	v_mul_f32_e32 v12, v20, v12
	v_mul_f32_e32 v20, v82, v70
	v_mul_f32_e32 v13, v20, v13
	v_mul_f32_e32 v20, v82, v72
	v_mul_f32_e32 v14, v20, v14
	v_mul_f32_e32 v20, v82, v24
	v_mul_f32_e32 v15, v20, v15
	v_mul_f32_e32 v20, v82, v28
	s_waitcnt lgkmcnt(0)
	v_mul_f32_e32 v16, v20, v16
	v_mul_f32_e32 v20, v82, v74
	v_mul_f32_e32 v17, v20, v17
	v_mul_f32_e32 v20, v82, v76
	v_mul_f32_e32 v18, v20, v18
	v_mul_f32_e32 v20, v82, v26
	v_mul_f32_e32 v19, v20, v19
	v_cvt_pk_bf16_f32 v146, v12, v13
	v_cvt_pk_bf16_f32 v147, v14, v15
	v_cvt_pk_bf16_f32 v148, v16, v17
	v_cvt_pk_bf16_f32 v149, v18, v19
	ds_read_b128 v[12:15], v39 offset:320
	ds_read_b128 v[16:19], v39 offset:336
	v_mul_f32_e32 v20, v82, v23
	s_waitcnt lgkmcnt(1)
; DI float lo_f(unsigned u) { return __uint_as_float(u << 16); }
; DI float hi_f(unsigned u) { return __uint_as_float(u & 0xffff0000u); }
; DI void attn_unit(LAS unsigned char* lds, const bf16* P, bf16* OG, float* LSE, const float* relb, int u) {
;     ...
;             qf[kk] = pack8(lo_f(q.x) * rs * g0[0], hi_f(q.x) * rs * g0[1], lo_f(q.y) * rs * g0[2], hi_f(q.y) * rs * g0[3], lo_f(q.z) * rs * g1[0], hi_f(q.z) * rs * g1[1], lo_f(q.w) * rs * g1[2], hi_f(q.w) * rs * g1[3]); }
;     }
;     f32x16 O[4];
; #pragma unroll
;     for (int dt = 0; dt < 4; ++dt)
; #pragma unroll
;         for (int i = 0; i < 16; ++i) O[dt][i] = 0.f;
;     float m = -1e30f, l = 0.f;
	v_mul_f32_e32 v12, v20, v12
	v_mul_f32_e32 v20, v82, v71
	v_mul_f32_e32 v13, v20, v13
	v_mul_f32_e32 v20, v82, v73
	v_mul_f32_e32 v14, v20, v14
	v_mul_f32_e32 v20, v82, v25
	v_mul_f32_e32 v15, v20, v15
	v_mul_f32_e32 v20, v82, v29
	s_waitcnt lgkmcnt(0)
	v_mul_f32_e32 v16, v20, v16
	v_mul_f32_e32 v20, v82, v75
	v_mul_f32_e32 v17, v20, v17
	v_mul_f32_e32 v20, v82, v77
	v_mul_f32_e32 v18, v20, v18
	v_mul_f32_e32 v20, v82, v27
	v_mul_f32_e32 v19, v20, v19
	v_cvt_pk_bf16_f32 v150, v12, v13
	v_cvt_pk_bf16_f32 v151, v14, v15
	v_cvt_pk_bf16_f32 v152, v16, v17
	v_cvt_pk_bf16_f32 v153, v18, v19
	ds_read_b128 v[12:15], v39 offset:384
	ds_read_b128 v[16:19], v39 offset:400
	s_waitcnt lgkmcnt(1)
	v_mul_f32_e32 v4, v4, v12
	v_mul_f32_e32 v6, v6, v13
	v_mul_f32_e32 v12, v82, v30
	v_mul_f32_e32 v13, v82, v32
	v_mul_f32_e32 v12, v12, v14
	v_mul_f32_e32 v13, v13, v15
	v_mul_f32_e32 v14, v82, v36
	v_mul_f32_e32 v15, v82, v78
	s_waitcnt lgkmcnt(0)
	v_mul_f32_e32 v14, v14, v16
	v_mul_f32_e32 v15, v15, v17
	v_mul_f32_e32 v16, v82, v80
	v_mul_f32_e32 v17, v82, v34
	v_mul_f32_e32 v16, v16, v18
	v_mul_f32_e32 v17, v17, v19
	v_cvt_pk_bf16_f32 v154, v4, v6
	v_cvt_pk_bf16_f32 v155, v12, v13
	v_cvt_pk_bf16_f32 v156, v14, v15
	v_cvt_pk_bf16_f32 v157, v16, v17
	ds_read_b128 v[12:15], v39 offset:448
	ds_read_b128 v[16:19], v39 offset:464
	v_and_b32_e32 v4, 16, v8
	v_lshrrev_b32_e32 v6, 2, v8
	v_and_or_b32 v2, v2, 12, v4
	s_waitcnt lgkmcnt(1)
	v_mul_f32_e32 v5, v5, v12
	v_mul_f32_e32 v7, v7, v13
	v_cvt_pk_bf16_f32 v158, v5, v7
	v_xor_b32_e32 v5, 1, v194
	v_cmp_lt_i32_e32 vcc, v5, v38
	v_mul_f32_e32 v12, v82, v31
	v_mul_f32_e32 v13, v82, v33
	v_cndmask_b32_e32 v5, v194, v5, vcc
	v_lshlrev_b32_e32 v186, 2, v5
	v_xor_b32_e32 v5, 2, v194
	v_cmp_lt_i32_e32 vcc, v5, v38
	v_lshlrev_b32_e32 v22, 1, v2
	v_and_or_b32 v2, v6, 3, v185
	v_cndmask_b32_e32 v5, v194, v5, vcc
	v_lshlrev_b32_e32 v187, 2, v5
	v_mov_b32_e32 v5, s26
	v_mul_f32_e32 v12, v12, v14
	v_mul_f32_e32 v13, v13, v15
	v_mul_f32_e32 v14, v82, v37
	v_mul_f32_e32 v15, v82, v79
	v_mad_u32_u24 v23, v2, s15, v5
	v_add_u32_e32 v2, s7, v10
	s_waitcnt lgkmcnt(0)
	v_mul_f32_e32 v14, v14, v16
	v_mul_f32_e32 v15, v15, v17
	v_mul_f32_e32 v16, v82, v81
	v_mul_f32_e32 v17, v82, v35
	v_subrev_u32_e32 v199, 64, v2
	v_lshl_add_u32 v2, v11, 2, s25
	v_mul_f32_e32 v16, v16, v18
	v_mul_f32_e32 v17, v17, v19
	v_sub_u32_e32 v2, v2, v0
	v_cvt_pk_bf16_f32 v159, v12, v13
	v_cvt_pk_bf16_f32 v160, v14, v15
	v_cvt_pk_bf16_f32 v161, v16, v17
	v_mad_u32_u24 v18, v10, s16, v5
	v_lshlrev_b32_e32 v19, 6, v9
	v_mad_u32_u24 v20, v10, s15, v5
	v_mad_u32_u24 v21, v11, s16, v5
	v_subrev_u32_e32 v2, s13, v2
	v_readlane_b32 s13, v254, 3
	v_mov_b32_e32 v16, v1
	v_mov_b32_e32 v17, v1
	v_add_u32_e32 v200, s13, v2
	v_mov_b32_e32 v2, v1
	v_mov_b32_e32 v4, v1
	v_mov_b32_e32 v5, v1
	v_mov_b32_e32 v6, v1
	v_mov_b32_e32 v7, v1
	v_mov_b32_e32 v8, v1
	v_mov_b32_e32 v9, v1
	v_mov_b32_e32 v10, v1
	v_mov_b32_e32 v11, v1
	v_mov_b32_e32 v12, v1
	v_mov_b32_e32 v13, v1
	v_mov_b32_e32 v14, v1
	v_mov_b32_e32 v15, v1
	v_add_u32_e32 v201, v18, v19
	v_add_u32_e32 v202, v20, v19
	v_add_u32_e32 v203, v21, v0
	v_add_u32_e32 v204, v23, v22
	v_mov_b64_e32 v[32:33], v[16:17]
	v_mov_b64_e32 v[48:49], v[16:17]
	v_mov_b64_e32 v[64:65], v[16:17]
	s_sub_i32 s13, s14, s23
	s_movk_i32 s14, 0xc0
	v_mov_b64_e32 v[30:31], v[14:15]
	v_mov_b64_e32 v[28:29], v[12:13]
	v_mov_b64_e32 v[26:27], v[10:11]
	v_mov_b64_e32 v[24:25], v[8:9]
	v_mov_b64_e32 v[22:23], v[6:7]
	v_mov_b64_e32 v[20:21], v[4:5]
	v_mov_b64_e32 v[18:19], v[2:3]
	v_mov_b64_e32 v[46:47], v[14:15]
	v_mov_b64_e32 v[44:45], v[12:13]
	v_mov_b64_e32 v[42:43], v[10:11]
	v_mov_b64_e32 v[40:41], v[8:9]
	v_mov_b64_e32 v[38:39], v[6:7]
	v_mov_b64_e32 v[36:37], v[4:5]
	v_mov_b64_e32 v[34:35], v[2:3]
	v_mov_b64_e32 v[62:63], v[14:15]
	v_mov_b64_e32 v[60:61], v[12:13]
	v_mov_b64_e32 v[58:59], v[10:11]
	v_mov_b64_e32 v[56:57], v[8:9]
	v_mov_b64_e32 v[54:55], v[6:7]
	v_mov_b64_e32 v[52:53], v[4:5]
	v_mov_b64_e32 v[50:51], v[2:3]

; __global__ void __launch_bounds__(512, 2) fwd_mega(Args a) {
	.amdhsa_kernel _Z8fwd_mega4Args
		.amdhsa_group_segment_fixed_size 0
		.amdhsa_private_segment_fixed_size 0
		.amdhsa_kernarg_size 424
		.amdhsa_user_sgpr_count 2
		.amdhsa_user_sgpr_dispatch_ptr 0
		.amdhsa_user_sgpr_queue_ptr 0
		.amdhsa_user_sgpr_kernarg_segment_ptr 1
		.amdhsa_user_sgpr_dispatch_id 0
		.amdhsa_user_sgpr_kernarg_preload_length 0
		.amdhsa_user_sgpr_kernarg_preload_offset 0
		.amdhsa_user_sgpr_private_segment_size 0
		.amdhsa_uses_dynamic_stack 0
		.amdhsa_enable_private_segment 0
		.amdhsa_system_sgpr_workgroup_id_x 1
		.amdhsa_system_sgpr_workgroup_id_y 0
		.amdhsa_system_sgpr_workgroup_id_z 0
		.amdhsa_system_sgpr_workgroup_info 0
		.amdhsa_system_vgpr_workitem_id 2
		.amdhsa_next_free_vgpr 256
		.amdhsa_next_free_sgpr 102
		.amdhsa_accum_offset 256
		.amdhsa_reserve_vcc 1
		.amdhsa_float_round_mode_32 0
		.amdhsa_float_round_mode_16_64 0
		.amdhsa_float_denorm_mode_32 3
		.amdhsa_float_denorm_mode_16_64 3
		.amdhsa_dx10_clamp 1
		.amdhsa_ieee_mode 1
		.amdhsa_fp16_overflow 0
		.amdhsa_tg_split 0
		.amdhsa_exception_fp_ieee_invalid_op 0
		.amdhsa_exception_fp_denorm_src 0
		.amdhsa_exception_fp_ieee_div_zero 0
		.amdhsa_exception_fp_ieee_overflow 0
		.amdhsa_exception_fp_ieee_underflow 0
		.amdhsa_exception_fp_ieee_inexact 0
		.amdhsa_exception_int_div_zero 0
	.end_amdhsa_kernel

; __global__ void __launch_bounds__(512, 2) fwd_mega(Args a) {
amdhsa.kernels:
  - .agpr_count:     0
    .args:
      - .offset:         0
        .size:           168
        .value_kind:     by_value
      - .offset:         168
        .size:           4
        .value_kind:     hidden_block_count_x
      - .offset:         172
        .size:           4
        .value_kind:     hidden_block_count_y
      - .offset:         176
        .size:           4
        .value_kind:     hidden_block_count_z
      - .offset:         180
        .size:           2
        .value_kind:     hidden_group_size_x
      - .offset:         182
        .size:           2
        .value_kind:     hidden_group_size_y
      - .offset:         184
        .size:           2
        .value_kind:     hidden_group_size_z
      - .offset:         186
        .size:           2
        .value_kind:     hidden_remainder_x
      - .offset:         188
        .size:           2
        .value_kind:     hidden_remainder_y
      - .offset:         190
        .size:           2
        .value_kind:     hidden_remainder_z
      - .offset:         208
        .size:           8
        .value_kind:     hidden_global_offset_x
      - .offset:         216
        .size:           8
        .value_kind:     hidden_global_offset_y
      - .offset:         224
        .size:           8
        .value_kind:     hidden_global_offset_z
      - .offset:         232
        .size:           2
        .value_kind:     hidden_grid_dims
      - .offset:         256
        .size:           8
        .value_kind:     hidden_multigrid_sync_arg
      - .offset:         288
        .size:           4
        .value_kind:     hidden_dynamic_lds_size
    .group_segment_fixed_size: 0
    .kernarg_segment_align: 8
    .kernarg_segment_size: 424
    .language:       OpenCL C
    .language_version:
      - 2
      - 0
    .max_flat_workgroup_size: 512
    .name:           _Z8fwd_mega4Args
    .private_segment_fixed_size: 0
    .sgpr_count:     108
    .sgpr_spill_count: 287
    .symbol:         _Z8fwd_mega4Args.kd
    .uniform_work_group_size: 1
    .uses_dynamic_stack: false
    .vgpr_count:     256
    .vgpr_spill_count: 0
    .wavefront_size: 64
